# attention: one bias MFMA per step instead of two (the second score tile's first QK MFMA takes the first tile's bias registers as SrcC; bit-identical)
# baseline (speedup 1.0000x reference)
.LBB0_1004:
	v_mfma_f32_32x32x16_bf16 v[68:83], v[246:249], v[250:253], 0
	v_mfma_f32_32x32x16_bf16 v[84:99], v[132:135], v[100:103], v[68:83]
	v_mfma_f32_32x32x16_bf16 v[68:83], v[136:139], v[100:103], v[68:83]
	v_add_u32_e32 v2, s45, v189
	ds_read_b128 v[184:187], v2 offset:96
	ds_read_b128 v[210:213], v2 offset:128
	ds_read_b128 v[214:217], v2 offset:6752
	ds_read_b128 v[218:221], v2 offset:160
	ds_read_b128 v[222:225], v2 offset:6784
	ds_read_b128 v[226:229], v2 offset:6816
	v_add_u32_e32 v2, s39, v200
	ds_read_b128 v[176:179], v2 offset:53248
	ds_read_b128 v[164:167], v2 offset:53280
	ds_read_b128 v[230:233], v2 offset:57856
	ds_read_b128 v[238:241], v2 offset:57888
	ds_read_b128 v[160:163], v2 offset:53312
	ds_read_b128 v[156:159], v2 offset:53344
	ds_read_b128 v[242:245], v2 offset:57920
	ds_read_b128 v[152:155], v2 offset:57952
	v_exp_f32_e32 v52, v52
	v_exp_f32_e32 v183, v36
	v_exp_f32_e32 v132, v53
	v_exp_f32_e32 v53, v54
	v_mfma_f32_32x32x16_bf16 v[68:83], v[144:147], v[104:107], v[68:83]
	v_exp_f32_e32 v54, v38
	v_exp_f32_e32 v36, v55
	v_exp_f32_e32 v55, v56
	v_exp_f32_e32 v56, v40
	v_mfma_f32_32x32x16_bf16 v[84:99], v[128:131], v[104:107], v[84:99]
	v_exp_f32_e32 v40, v39
	v_exp_f32_e32 v38, v57
	v_exp_f32_e32 v57, v58
	v_exp_f32_e32 v58, v41
	v_mfma_f32_32x32x16_bf16 v[68:83], v[140:143], v[108:111], v[68:83]
	v_add_u32_e32 v181, s44, v189
	ds_read_b128 v[144:147], v181
	ds_read_b128 v[172:175], v181 offset:32
	ds_read_b128 v[136:139], v181 offset:6656
	ds_read_b128 v[168:171], v181 offset:64
	ds_read_b128 v[148:151], v181 offset:6688
	ds_read_b128 v[140:143], v181 offset:6720
	v_exp_f32_e32 v2, v37
	v_mfma_f32_32x32x16_bf16 v[84:99], v[124:127], v[108:111], v[84:99]
	v_exp_f32_e32 v124, v59
	v_exp_f32_e32 v41, v60
	v_add_f32_e32 v133, v52, v183
	v_add_f32_e32 v37, v53, v54
	s_waitcnt lgkmcnt(14)
	v_mfma_f32_32x32x16_bf16 v[68:83], v[214:217], v[112:115], v[68:83]
	v_exp_f32_e32 v214, v42
	v_exp_f32_e32 v59, v44
	v_exp_f32_e32 v60, v43
	v_exp_f32_e32 v126, v61
	v_mfma_f32_32x32x16_bf16 v[84:99], v[184:187], v[112:115], v[84:99]
	v_exp_f32_e32 v61, v62
	v_exp_f32_e32 v62, v45
	v_exp_f32_e32 v128, v63
	v_exp_f32_e32 v63, v64
	v_mfma_f32_32x32x16_bf16 v[68:83], v[222:225], v[116:119], v[68:83]
	v_exp_f32_e32 v216, v48
	v_exp_f32_e32 v64, v47
	v_exp_f32_e32 v130, v65
	v_mfma_f32_32x32x16_bf16 v[84:99], v[210:213], v[116:119], v[84:99]
	v_exp_f32_e32 v65, v66
	v_exp_f32_e32 v215, v46
	v_exp_f32_e32 v185, v50
	v_mfma_f32_32x32x16_bf16 v[68:83], v[226:229], v[120:123], v[68:83]
	v_exp_f32_e32 v66, v49
	v_exp_f32_e32 v134, v67
	v_add_f32_e32 v39, v55, v56
	v_add_f32_e32 v125, v57, v214
	v_mfma_f32_32x32x16_bf16 v[84:99], v[218:221], v[120:123], v[84:99]
	v_add_f32_e32 v127, v41, v59
	v_add_f32_e32 v129, v61, v215
	v_add_f32_e32 v131, v63, v216
	v_add_f32_e32 v135, v65, v185
	v_exp_f32_e32 v184, v51
	v_cvt_pk_bf16_f32 v42, v52, v132
	v_cvt_pk_bf16_f32 v43, v53, v36
	v_cvt_pk_bf16_f32 v44, v55, v38
	v_cvt_pk_bf16_f32 v45, v57, v124
	v_cvt_pk_bf16_f32 v46, v41, v126
	v_cvt_pk_bf16_f32 v47, v61, v128
	s_waitcnt lgkmcnt(11)
	v_mfma_f32_32x32x16_bf16 v[4:19], v[42:45], v[230:233], v[4:19]
	v_cvt_pk_bf16_f32 v48, v63, v130
	v_cvt_pk_bf16_f32 v49, v65, v134
	v_cvt_pk_bf16_f32 v50, v183, v2
	v_cvt_pk_bf16_f32 v51, v54, v40
	v_cvt_pk_bf16_f32 v52, v56, v58
	v_cvt_pk_bf16_f32 v53, v214, v60
	v_mfma_f32_32x32x16_bf16 v[20:35], v[42:45], v[176:179], v[20:35]
	v_cvt_pk_bf16_f32 v54, v59, v62
	v_cvt_pk_bf16_f32 v55, v215, v64
	v_cvt_pk_bf16_f32 v56, v216, v66
	v_cvt_pk_bf16_f32 v57, v185, v184
	s_add_i32 s14, s46, 5
	s_min_u32 s14, s14, s37
	s_add_i32 s15, s46, 3
	s_min_u32 s46, s15, s37
	s_mulk_i32 s14, 0x3000
	s_add_u32 s14, s10, s14
	s_addc_u32 s15, s11, 0
	s_lshl_b32 s46, s46, 13
	s_add_u32 s46, s12, s46
	s_addc_u32 s47, s13, 0
	s_add_i32 m0, s22, s45
	s_and_b64 s[48:49], s[4:5], exec
	s_waitcnt vmcnt(3) lgkmcnt(0)
	s_barrier
	v_mfma_f32_32x32x16_bf16 v[4:19], v[46:49], v[238:241], v[4:19]
	global_load_lds_dwordx4 v190, s[14:15]
	s_cselect_b32 s15, s15, s47
	s_cselect_b32 s14, s14, s46
	s_cselect_b32 s98, s45, s39
	s_add_i32 m0, s21, s98
	s_add_i32 s98, s23, s39
	global_load_lds_dwordx4 v192, s[14:15]
	s_add_i32 m0, s98, 0xd000
	s_nop 0
	global_load_lds_dwordx4 v194, s[46:47]
	v_max3_f32 v41, v84, v68, v85
	v_max3_f32 v59, v92, v76, v93
	v_add_f32_e32 v132, v132, v2
	v_max3_f32 v41, v41, v69, v86
	v_max3_f32 v59, v59, v77, v94
	v_mfma_f32_32x32x16_bf16 v[20:35], v[46:49], v[164:167], v[20:35]
	s_nop 0
	v_max3_f32 v41, v41, v70, v87
	v_max3_f32 v41, v41, v71, v88
	v_max3_f32 v59, v59, v78, v95
	v_max3_f32 v41, v41, v72, v89
	v_max3_f32 v59, v59, v79, v96
	s_nop 0
	v_max3_f32 v41, v41, v73, v90
	v_max3_f32 v183, v41, v74, v91
	v_mfma_f32_32x32x16_bf16 v[4:19], v[50:53], v[242:245], v[4:19]
	v_add_f32_e32 v41, v132, v133
	v_max3_f32 v59, v59, v80, v97
	v_add_f32_e64 v36, v36, v40
	v_add_f32_e64 v37, v37, v41
	v_max3_f32 v59, v59, v81, v98
	v_max3_f32 v186, v59, v82, v99
	v_add_f32_e32 v59, v36, v37
	v_add_f32_e32 v36, v38, v58
	v_add_f32_e32 v37, v39, v59
	v_mfma_f32_32x32x16_bf16 v[20:35], v[50:53], v[160:163], v[20:35]
	v_add_f32_e32 v61, v36, v37
	v_add_f32_e32 v36, v124, v60
	v_add_f32_e32 v37, v125, v61
	v_add_f32_e32 v63, v36, v37
	v_add_f32_e32 v36, v126, v62
	v_add_f32_e32 v37, v127, v63
	v_add_f32_e32 v65, v36, v37
	v_add_f32_e32 v36, v128, v64
	v_add_f32_e32 v37, v129, v65
	v_mfma_f32_32x32x16_bf16 v[20:35], v[54:57], v[156:159], v[20:35]
	v_add_f32_e32 v67, v36, v37
	v_add_f32_e32 v36, v130, v66
	v_add_f32_e32 v37, v131, v67
	v_add_f32_e32 v185, v36, v37
	v_add_f32_e32 v36, v134, v184
	v_add_f32_e32 v37, v135, v185
	v_add_f32_e32 v2, v36, v37
	v_max3_f32 v36, v183, v75, v186
	v_add_f32_e32 v2, v209, v2
	v_mfma_f32_32x32x16_bf16 v[4:19], v[54:57], v[152:155], v[4:19]
	v_max3_f32 v36, v36, v83, v36
	s_nop 0
	v_mov_b32_e32 v38, v36
	s_nop 0
	s_nop 0
	v_permlane32_swap_b32_e32 v36, v38
	v_max3_f32 v36, v36, v38, v36
	s_nop 0
	v_cmp_lt_f32_e32 vcc, s56, v36
	s_cbranch_vccz .LBB0_1008
	s_nop 0
	v_add_f32_e32 v210, v180, v36
	v_cvt_pk_bf16_f32 v210, v210, v210
	v_lshlrev_b32_e32 v210, 16, v210
	v_cndmask_b32_e32 v210, v180, v210, vcc
	v_sub_f32_e32 v36, v180, v210
	v_sub_f32_e32 v186, v210, v180
	v_xor_b32_e32 v250, 0x80000000, v210
	v_min_f32_e32 v36, 0, v36
	v_lshrrev_b32_e32 v250, 16, v250
	v_exp_f32_e32 v36, v36
	v_cndmask_b32_e64 v250, 0, v250, s[2:3]
	s_and_saveexec_b64 s[14:15], s[2:3]
	ds_write_b32 v202, v36
	s_or_b64 exec, exec, s[14:15]
	v_mul_f32_e32 v2, v2, v36
	ds_read_b32 v36, v1
	ds_read_b32 v37, v1 offset:4
	ds_read_b32 v38, v1 offset:8
	ds_read_b32 v39, v1 offset:12
	ds_read_b32 v40, v1 offset:32
	ds_read_b32 v41, v1 offset:36
	ds_read_b32 v42, v1 offset:40
	ds_read_b32 v43, v1 offset:44
	ds_read_b32 v44, v1 offset:64
	ds_read_b32 v45, v1 offset:68
	ds_read_b32 v46, v1 offset:72
	ds_read_b32 v47, v1 offset:76
	ds_read_b32 v48, v1 offset:96
	ds_read_b32 v49, v1 offset:100
	ds_read_b32 v50, v1 offset:104
	ds_read_b32 v51, v1 offset:108
	s_waitcnt lgkmcnt(0)
	v_pk_mul_f32 v[20:21], v[20:21], v[36:37]
	v_pk_mul_f32 v[22:23], v[22:23], v[38:39]
	v_pk_mul_f32 v[24:25], v[24:25], v[40:41]
	v_pk_mul_f32 v[26:27], v[26:27], v[42:43]
	v_pk_mul_f32 v[28:29], v[28:29], v[44:45]
	v_pk_mul_f32 v[30:31], v[30:31], v[46:47]
	v_pk_mul_f32 v[32:33], v[32:33], v[48:49]
	v_pk_mul_f32 v[34:35], v[34:35], v[50:51]
	v_pk_mul_f32 v[4:5], v[4:5], v[36:37]
	v_pk_mul_f32 v[6:7], v[6:7], v[38:39]
	v_pk_mul_f32 v[8:9], v[8:9], v[40:41]
	v_pk_mul_f32 v[10:11], v[10:11], v[42:43]
	v_pk_mul_f32 v[12:13], v[12:13], v[44:45]
	v_pk_mul_f32 v[14:15], v[14:15], v[46:47]
	v_pk_mul_f32 v[16:17], v[16:17], v[48:49]
	v_pk_mul_f32 v[18:19], v[18:19], v[50:51]
	v_sub_f32_e32 v68, v68, v186
	v_sub_f32_e32 v69, v69, v186
	v_sub_f32_e32 v70, v70, v186
	v_sub_f32_e32 v71, v71, v186
	v_sub_f32_e32 v72, v72, v186
	v_sub_f32_e32 v73, v73, v186
	v_sub_f32_e32 v74, v74, v186
	v_sub_f32_e32 v75, v75, v186
	v_sub_f32_e32 v76, v76, v186
	v_sub_f32_e32 v77, v77, v186
	v_sub_f32_e32 v78, v78, v186
	v_sub_f32_e32 v79, v79, v186
	v_sub_f32_e32 v80, v80, v186
	v_sub_f32_e32 v81, v81, v186
	v_sub_f32_e32 v82, v82, v186
	v_sub_f32_e32 v83, v83, v186
	v_sub_f32_e32 v84, v84, v186
	v_sub_f32_e32 v85, v85, v186
	v_sub_f32_e32 v86, v86, v186
	v_sub_f32_e32 v87, v87, v186
	v_sub_f32_e32 v88, v88, v186
	v_sub_f32_e32 v89, v89, v186
	v_sub_f32_e32 v90, v90, v186
	v_sub_f32_e32 v91, v91, v186
	v_sub_f32_e32 v92, v92, v186
	v_sub_f32_e32 v93, v93, v186
	v_sub_f32_e32 v94, v94, v186
	v_sub_f32_e32 v95, v95, v186
	v_sub_f32_e32 v96, v96, v186
	v_sub_f32_e32 v97, v97, v186
	v_sub_f32_e32 v98, v98, v186
	v_sub_f32_e32 v99, v99, v186
	s_mov_b32 s56, 0x41000000
	s_branch .LBB0_1009

; #define AT_KRD(dst, koff, ks0) do { const LAS unsigned char* Kl = Kr + (koff); \
;             _Pragma("unroll") for (int ks = 0; ks < 3; ++ks) { dst[2 * ks] = *(const LAS bf16x8_t*)(Kl + ((ks0) + ks) * 32); dst[2 * ks + 1] = *(const LAS bf16x8_t*)(Kl + 32 * AT_KP + ((ks0) + ks) * 32); } } while (0)
; #define AT_KMM(P0, P1, src, ks0) do { _Pragma("unroll") for (int ks = 0; ks < 3; ++ks) { \
;             P0 = __builtin_amdgcn_mfma_f32_32x32x16_bf16(src[2 * ks], qf[(ks0) + ks], P0, 0, 0, 0); P1 = __builtin_amdgcn_mfma_f32_32x32x16_bf16(src[2 * ks + 1], qf[(ks0) + ks], P1, 0, 0, 0); } } while (0)
; #define AT_ZERO(P0, P1) do { _Pragma("unroll") for (int r = 0; r < 16; ++r) { P0[r] = 0.f; P1[r] = 0.f; } } while (0)
; __device__ __forceinline__ void ph_attn(Frame& F) {
;     ...
;         int kq = AT_KB, kn = 2 * AT_KB, k3 = 3 * AT_KB, kw = 0, vn = 0, v1 = AT_VB, vw = 2 * AT_VB;
;         { bf16x8_t kg[6]; AT_KRD(kf, 0, 0); AT_KRD(kg, 0, 3); AT_ZERO(pA0, pA1); AT_KMM(pA0, pA1, kf, 0); AT_KMM(pA0, pA1, kg, 3); AT_KRD(kf, AT_KB, 0); }
;         __syncthreads();
;         if (AT_PRIO && __builtin_amdgcn_readfirstlane(wave) >= 4) __builtin_amdgcn_s_setprio(1);
;         for (int t = 0; t < NT; t += 2) {
;             AT_STEP(pA0, pA1, pB0, pB1, t);
;             AT_STEP(pB0, pB1, pA0, pA1, t + 1);
;         }
.LBB0_1009:
	v_mfma_f32_32x32x16_bf16 v[36:51], v[246:249], v[250:253], 0
	v_mfma_f32_32x32x16_bf16 v[52:67], v[144:147], v[100:103], v[36:51]
	v_mfma_f32_32x32x16_bf16 v[36:51], v[136:139], v[100:103], v[36:51]
	v_add_u32_e32 v255, s43, v200
	ds_read_b128 v[212:215], v181 offset:96
	ds_read_b128 v[216:219], v181 offset:128
	ds_read_b128 v[220:223], v181 offset:6752
	ds_read_b128 v[224:227], v181 offset:160
	ds_read_b128 v[228:231], v181 offset:6784
	ds_read_b128 v[238:241], v181 offset:6816
	ds_read_b128 v[160:163], v255 offset:53248
	ds_read_b128 v[164:167], v255 offset:53280
	ds_read_b128 v[184:187], v255 offset:57856
	ds_read_b128 v[180:183], v255 offset:57888
	ds_read_b128 v[156:159], v255 offset:53312
	ds_read_b128 v[152:155], v255 offset:53344
	v_add_u32_e32 v209, s41, v189
	v_mfma_f32_32x32x16_bf16 v[36:51], v[148:151], v[104:107], v[36:51]
	ds_read_b128 v[176:179], v255 offset:57920
	ds_read_b128 v[148:151], v255 offset:57952
	v_exp_f32_e32 v211, v84
	v_exp_f32_e32 v232, v68
	v_exp_f32_e32 v233, v85
	v_exp_f32_e32 v235, v69
	v_add_f32_e32 v68, v211, v232
	v_add_f32_e32 v69, v233, v235
	v_add_f32_e32 v68, v69, v68
	v_mfma_f32_32x32x16_bf16 v[52:67], v[172:175], v[104:107], v[52:67]
	v_exp_f32_e32 v173, v70
	v_exp_f32_e32 v172, v86
	v_exp_f32_e32 v174, v87
	v_exp_f32_e32 v175, v71
	v_add_f32_e32 v69, v172, v173
	v_add_f32_e32 v68, v69, v68
	v_mfma_f32_32x32x16_bf16 v[52:67], v[168:171], v[108:111], v[52:67]
	v_add_f32_e32 v69, v174, v175
	v_add_f32_e32 v168, v69, v68
	v_exp_f32_e32 v71, v88
	v_exp_f32_e32 v85, v72
	v_exp_f32_e32 v70, v89
	v_exp_f32_e32 v84, v73
	v_exp_f32_e32 v73, v90
	v_exp_f32_e32 v87, v74
	v_exp_f32_e32 v72, v91
	v_exp_f32_e32 v86, v75
	v_pk_add_f32 v[68:69], v[70:71], v[84:85]
	v_mfma_f32_32x32x16_bf16 v[36:51], v[140:143], v[108:111], v[36:51]
	v_add_f32_e32 v69, v69, v168
	v_add_f32_e32 v74, v68, v69
	v_add_f32_e64 v68, v72, v86
	v_add_f32_e64 v69, v73, v87
	ds_read_b128 v[132:135], v209
	ds_read_b128 v[128:131], v209 offset:32
	ds_read_b128 v[136:139], v209 offset:6656
	ds_read_b128 v[124:127], v209 offset:64
	v_add_f32_e32 v69, v69, v74
	v_add_f32_e32 v168, v68, v69
	v_exp_f32_e32 v75, v92
	v_exp_f32_e32 v89, v76
	v_exp_f32_e32 v74, v93
	v_exp_f32_e32 v88, v77
	v_exp_f32_e32 v77, v94
	s_waitcnt lgkmcnt(12)
	v_mfma_f32_32x32x16_bf16 v[36:51], v[220:223], v[112:115], v[36:51]
	v_exp_f32_e32 v91, v78
	v_exp_f32_e32 v76, v95
	v_exp_f32_e32 v90, v79
	v_pk_add_f32 v[68:69], v[74:75], v[88:89]
	ds_read_b128 v[144:147], v209 offset:6688
	ds_read_b128 v[140:143], v209 offset:6720
	v_mfma_f32_32x32x16_bf16 v[52:67], v[212:215], v[112:115], v[52:67]
	v_add_f32_e32 v69, v69, v168
	v_add_f32_e32 v78, v68, v69
	v_add_f32_e64 v68, v76, v90
	v_add_f32_e64 v69, v77, v91
	v_add_f32_e32 v69, v69, v78
	v_add_f32_e32 v168, v68, v69
	v_mfma_f32_32x32x16_bf16 v[36:51], v[228:231], v[116:119], v[36:51]
	v_exp_f32_e32 v79, v96
	v_exp_f32_e32 v93, v80
	v_exp_f32_e32 v78, v97
	v_exp_f32_e32 v92, v81
	v_mfma_f32_32x32x16_bf16 v[52:67], v[216:219], v[116:119], v[52:67]
	v_exp_f32_e32 v95, v98
	v_exp_f32_e32 v97, v82
	v_exp_f32_e32 v94, v99
	v_mfma_f32_32x32x16_bf16 v[36:51], v[238:241], v[120:123], v[36:51]
	v_exp_f32_e32 v96, v83
	v_pk_add_f32 v[68:69], v[78:79], v[92:93]
	s_nop 0
	v_add_f32_e32 v69, v69, v168
	v_add_f32_e32 v80, v68, v69
	v_pk_add_f32 v[68:69], v[94:95], v[96:97]
	v_mfma_f32_32x32x16_bf16 v[52:67], v[224:227], v[120:123], v[52:67]
	v_add_f32_e32 v69, v69, v80
	v_add_f32_e32 v68, v68, v69
	v_add_f32_e32 v209, v2, v68
	v_cvt_pk_bf16_f32 v68, v211, v233
	v_cvt_pk_bf16_f32 v69, v172, v174
	v_cvt_pk_bf16_f32 v70, v71, v70
	v_cvt_pk_bf16_f32 v71, v73, v72
	v_cvt_pk_bf16_f32 v80, v75, v74
	v_cvt_pk_bf16_f32 v81, v77, v76
	s_waitcnt lgkmcnt(11)
	v_mfma_f32_32x32x16_bf16 v[4:19], v[68:71], v[184:187], v[4:19]
	v_cvt_pk_bf16_f32 v82, v79, v78
	v_cvt_pk_bf16_f32 v83, v95, v94
	v_cvt_pk_bf16_f32 v76, v232, v235
	v_cvt_pk_bf16_f32 v77, v173, v175
	v_cvt_pk_bf16_f32 v78, v85, v84
	v_cvt_pk_bf16_f32 v79, v87, v86
	v_mfma_f32_32x32x16_bf16 v[20:35], v[68:71], v[160:163], v[20:35]
	v_cvt_pk_bf16_f32 v72, v89, v88
	v_cvt_pk_bf16_f32 v73, v91, v90
	v_cvt_pk_bf16_f32 v74, v93, v92
	v_cvt_pk_bf16_f32 v75, v97, v96
	s_cmp_ge_u32 s42, s36
	s_cbranch_scc1 .Lattn_exit
	s_mov_b32 s14, s41
	s_mov_b32 s15, s38
	s_mov_b32 s41, s45
	s_mov_b32 s38, s44
	s_mov_b32 s44, s40
	s_mov_b32 s40, s43
	s_mov_b32 s46, s42
	s_add_i32 s42, s46, 4
	s_min_u32 s43, s42, s37
	s_add_i32 s42, s46, 2
	s_min_u32 s45, s42, s37
	s_mulk_i32 s43, 0x3000
	s_add_u32 s48, s10, s43
	s_addc_u32 s49, s11, 0
	s_lshl_b32 s43, s45, 13
	s_add_u32 s50, s12, s43
	s_addc_u32 s51, s13, 0
	s_add_i32 m0, s22, s38
	s_and_b64 s[52:53], s[4:5], exec
	s_waitcnt vmcnt(3) lgkmcnt(0)
	s_barrier
	s_branch .LBB0_999

; __global__ void __launch_bounds__(NWAVES * 64, 2) mk_fwd(Args args) {
	.amdhsa_kernel _Z6mk_fwd4Args
		.amdhsa_group_segment_fixed_size 0
		.amdhsa_private_segment_fixed_size 0
		.amdhsa_kernarg_size 528
		.amdhsa_user_sgpr_count 2
		.amdhsa_user_sgpr_dispatch_ptr 0
		.amdhsa_user_sgpr_queue_ptr 0
		.amdhsa_user_sgpr_kernarg_segment_ptr 1
		.amdhsa_user_sgpr_dispatch_id 0
		.amdhsa_user_sgpr_kernarg_preload_length 0
		.amdhsa_user_sgpr_kernarg_preload_offset 0
		.amdhsa_user_sgpr_private_segment_size 0
		.amdhsa_uses_dynamic_stack 0
		.amdhsa_enable_private_segment 0
		.amdhsa_system_sgpr_workgroup_id_x 1
		.amdhsa_system_sgpr_workgroup_id_y 0
		.amdhsa_system_sgpr_workgroup_id_z 0
		.amdhsa_system_sgpr_workgroup_info 0
		.amdhsa_system_vgpr_workitem_id 0
		.amdhsa_next_free_vgpr 256
		.amdhsa_next_free_sgpr 102
		.amdhsa_accum_offset 256
		.amdhsa_reserve_vcc 1
		.amdhsa_float_round_mode_32 0
		.amdhsa_float_round_mode_16_64 0
		.amdhsa_float_denorm_mode_32 3
		.amdhsa_float_denorm_mode_16_64 3
		.amdhsa_dx10_clamp 1
		.amdhsa_ieee_mode 1
		.amdhsa_fp16_overflow 0
		.amdhsa_tg_split 0
		.amdhsa_exception_fp_ieee_invalid_op 0
		.amdhsa_exception_fp_denorm_src 0
		.amdhsa_exception_fp_ieee_div_zero 0
		.amdhsa_exception_fp_ieee_overflow 0
		.amdhsa_exception_fp_ieee_underflow 0
		.amdhsa_exception_fp_ieee_inexact 0
		.amdhsa_exception_int_div_zero 0
	.end_amdhsa_kernel

; __global__ void __launch_bounds__(NWAVES * 64, 2) mk_fwd(Args args) {
amdhsa.kernels:
  - .agpr_count:     0
    .args:
      - .offset:         0
        .size:           272
        .value_kind:     by_value
      - .offset:         272
        .size:           4
        .value_kind:     hidden_block_count_x
      - .offset:         276
        .size:           4
        .value_kind:     hidden_block_count_y
      - .offset:         280
        .size:           4
        .value_kind:     hidden_block_count_z
      - .offset:         284
        .size:           2
        .value_kind:     hidden_group_size_x
      - .offset:         286
        .size:           2
        .value_kind:     hidden_group_size_y
      - .offset:         288
        .size:           2
        .value_kind:     hidden_group_size_z
      - .offset:         290
        .size:           2
        .value_kind:     hidden_remainder_x
      - .offset:         292
        .size:           2
        .value_kind:     hidden_remainder_y
      - .offset:         294
        .size:           2
        .value_kind:     hidden_remainder_z
      - .offset:         312
        .size:           8
        .value_kind:     hidden_global_offset_x
      - .offset:         320
        .size:           8
        .value_kind:     hidden_global_offset_y
      - .offset:         328
        .size:           8
        .value_kind:     hidden_global_offset_z
      - .offset:         336
        .size:           2
        .value_kind:     hidden_grid_dims
      - .offset:         392
        .size:           4
        .value_kind:     hidden_dynamic_lds_size
    .group_segment_fixed_size: 0
    .kernarg_segment_align: 8
    .kernarg_segment_size: 528
    .language:       OpenCL C
    .language_version:
      - 2
      - 0
    .max_flat_workgroup_size: 512
    .name:           _Z6mk_fwd4Args
    .private_segment_fixed_size: 0
    .sgpr_count:     108
    .sgpr_spill_count: 28
    .symbol:         _Z6mk_fwd4Args.kd
    .uniform_work_group_size: 1
    .uses_dynamic_stack: false
    .vgpr_count:     256
    .vgpr_spill_count: 0
    .wavefront_size: 64
